# C1c: DFT combine pass reorder (second item's loads before the first consumer wait), compensated inside the earlier dead pad so every address from the combine loop's end on is unchanged; on top of K1+R
# speedup vs baseline: 1.0082x; 1.0082x over previous
; __device__ __forceinline__ unsigned cvt_pk_bf16(float lo, float hi) { f32x2_t v = {lo, hi}; bf16x2_t b = __builtin_convertvector(v, bf16x2_t); return __builtin_bit_cast(unsigned, b); }
; __device__ __forceinline__ float silu_f(float x) { return x * __builtin_amdgcn_rcpf(1.0f + __builtin_amdgcn_exp2f(-x * LOG2E)); }
; __device__ __forceinline__ void ffn_fixup(const Args& a, int layer, int nrows, int gt, int NT) {
;     ...
;     for (int idx = gt; idx < nblk * 2 * (DFF / 4); idx += NT) {
;         const int c4 = idx % (DFF / 4), bw = idx / (DFF / 4), blk = bw >> 1, which = bw & 1, col = 4 * c4;
;         const int row = blk * 64 + (which ? 63 : 0);
;         const int sb = row < MX ? (blk & 31) : ((blk - MX / 64) & 3), nsb = row < MX ? 32 : 4;
;         const _Float16* sp = SIDE + ((size_t)(blk * 2 + which) * 3) * DFF + col;
;         f32x4 cv = __builtin_convertvector(*(const sh4*)sp, f32x4); const f32x4 vv = __builtin_convertvector(*(const sh4*)(sp + 2 * DFF), f32x4);
;         if (which == 0 && sb > 0) { const f32x4 gl = __builtin_convertvector(*(const sh4*)(SIDE + ((size_t)((blk - 1) * 2 + 1) * 3 + 1) * DFF + col), f32x4); cv += *(const f32x4*)(cw + col) * gl; }
;         if (which == 1 && sb < nsb - 1) { const f32x4 gf = __builtin_convertvector(*(const sh4*)(SIDE + ((size_t)((blk + 1) * 2 + 0) * 3 + 1) * DFF + col), f32x4); cv += *(const f32x4*)(cw + 2 * DFF + col) * gf; }
;         const f32x4 vs = vv * (-LOG2E);
;         u32x2 w; w.x = cvt_pk_bf16(silu_f(cv[0]) * vs[0], silu_f(cv[1]) * vs[1]); w.y = cvt_pk_bf16(silu_f(cv[2]) * vs[2], silu_f(cv[3]) * vs[3]);
;         *(u32x2*)(ACT + (size_t)row * DFF + col) = w;
;     }
.Lfx_nofma:
	s_mov_b64 exec, s[12:13]
	s_branch .LBB0_109
	s_nop 0
	s_nop 0
	s_nop 0
	s_nop 0
	s_nop 0
	s_nop 0
	s_nop 0
	s_nop 0
	s_nop 0
	s_nop 0
	s_nop 0
	s_nop 0
	s_nop 0
.LBB0_114:
	s_or_b64 exec, exec, s[0:1]
	s_mov_b64 s[0:1], 0
